# pass1/pass3 logf: final ln2 accumulate and copy folded into one v_fma (bit-identical), on top of v41
# baseline (speedup 1.0000x reference)
; __device__ __forceinline__ void hgrn_pass3_all(LAS unsigned char* lds, const unsigned char* R, const bf16_t* ST, bf16_t* O, const float* ng, const float* lbp, int u0, int ustep, int tid) {
;     ...
;     HG_CUMSUM(tot)
.LBB0_98:
	v_mul_f32_e32 v119, 0xbfb8aa3b, v227
	v_exp_f32_e32 v119, v119
	s_mov_b32 s14, 0x800000
	v_mul_f32_e32 v226, 0xbfb8aa3b, v226
	v_exp_f32_e32 v226, v226
	v_add_f32_e32 v119, 1.0, v119
	v_rcp_f32_e32 v119, v119
	s_mov_b32 s15, 0x3f317217
	v_add_f32_e32 v226, 1.0, v226
	v_rcp_f32_e32 v226, v226
	s_mov_b32 s16, 0x7f800000
	v_mul_f32_e32 v230, 0xbfb8aa3b, v230
	v_exp_f32_e32 v230, v230
	v_mul_f32_e32 v232, 0xbfb8aa3b, v232
	v_exp_f32_e32 v232, v232
	v_mul_f32_e32 v234, 0xbfb8aa3b, v234
	v_add_f32_e32 v230, 1.0, v230
	v_rcp_f32_e32 v230, v230
	v_add_f32_e32 v232, 1.0, v232
	v_rcp_f32_e32 v232, v232
	v_exp_f32_e32 v234, v234
	v_mul_f32_e32 v236, 0xbfb8aa3b, v236
	v_exp_f32_e32 v236, v236
	v_mul_f32_e32 v225, 0xbfb8aa3b, v225
	v_add_f32_e32 v234, 1.0, v234
	v_rcp_f32_e32 v234, v234
	v_add_f32_e32 v236, 1.0, v236
	v_rcp_f32_e32 v236, v236
	v_exp_f32_e32 v225, v225
	v_mul_f32_e32 v224, 0xbfb8aa3b, v224
	v_exp_f32_e32 v224, v224
	v_mul_f32_e32 v223, 0xbfb8aa3b, v223
	v_add_f32_e32 v225, 1.0, v225
	v_rcp_f32_e32 v225, v225
	v_add_f32_e32 v224, 1.0, v224
	v_rcp_f32_e32 v224, v224
	v_exp_f32_e32 v223, v223
	v_mul_f32_e32 v222, 0xbfb8aa3b, v222
	v_exp_f32_e32 v222, v222
	v_mul_f32_e32 v135, 0xbfb8aa3b, v135
	v_add_f32_e32 v223, 1.0, v223
	v_rcp_f32_e32 v223, v223
	v_add_f32_e32 v222, 1.0, v222
	v_rcp_f32_e32 v222, v222
	v_exp_f32_e32 v135, v135
	v_mul_f32_e32 v134, 0xbfb8aa3b, v134
	v_exp_f32_e32 v134, v134
	v_mul_f32_e32 v133, 0xbfb8aa3b, v133
	v_add_f32_e32 v135, 1.0, v135
	v_rcp_f32_e32 v135, v135
	v_add_f32_e32 v134, 1.0, v134
	v_rcp_f32_e32 v134, v134
	v_exp_f32_e32 v133, v133
	v_mul_f32_e32 v132, 0xbfb8aa3b, v132
	v_exp_f32_e32 v132, v132
	v_mul_f32_e32 v131, 0xbfb8aa3b, v131
	v_add_f32_e32 v133, 1.0, v133
	v_rcp_f32_e32 v133, v133
	v_add_f32_e32 v132, 1.0, v132
	v_rcp_f32_e32 v132, v132
	v_exp_f32_e32 v131, v131
	v_mul_f32_e32 v130, 0xbfb8aa3b, v130
	v_exp_f32_e32 v130, v130
	v_add_f32_e32 v131, 1.0, v131
	v_rcp_f32_e32 v131, v131
	v_add_f32_e32 v130, 1.0, v130
	v_rcp_f32_e32 v130, v130
	s_waitcnt vmcnt(58)
	v_sub_f32_e32 v229, 1.0, v228
	v_fma_f32 v119, v119, v229, v228
	v_max_f32_e32 v119, 0x1e3ce508, v119
	v_fma_f32 v226, v226, v229, v228
	v_max_f32_e32 v226, 0x1e3ce508, v226
	v_log_f32_e32 v227, v119
	v_fma_f32 v230, v230, v229, v228
	v_max_f32_e32 v230, 0x1e3ce508, v230
	v_fma_f32 v232, v232, v229, v228
	v_mul_f32_e32 v231, 0x3f317217, v227
	v_fma_f32 v231, v227, s15, -v231
	v_fmac_f32_e32 v231, 0x3377d1cf, v227
	v_max_f32_e32 v232, 0x1e3ce508, v232
	v_fma_f32 v234, v234, v229, v228
	v_fma_f32 v227, v227, s15, v231
	v_max_f32_e32 v234, 0x1e3ce508, v234
	v_log_f32_e32 v231, v226
	v_fma_f32 v236, v236, v229, v228
	v_max_f32_e32 v236, 0x1e3ce508, v236
	v_fma_f32 v225, v225, v229, v228
	v_mul_f32_e32 v233, 0x3f317217, v231
	v_fma_f32 v233, v231, s15, -v233
	v_fmac_f32_e32 v233, 0x3377d1cf, v231
	v_max_f32_e32 v225, 0x1e3ce508, v225
	v_fma_f32 v224, v224, v229, v228
	v_fma_f32 v231, v231, s15, v233
	v_max_f32_e32 v224, 0x1e3ce508, v224
	v_log_f32_e32 v233, v230
	v_fma_f32 v223, v223, v229, v228
	v_max_f32_e32 v223, 0x1e3ce508, v223
	v_fma_f32 v222, v222, v229, v228
	v_mul_f32_e32 v235, 0x3f317217, v233
	v_fma_f32 v235, v233, s15, -v235
	v_fmac_f32_e32 v235, 0x3377d1cf, v233
	v_max_f32_e32 v222, 0x1e3ce508, v222
	v_fma_f32 v135, v135, v229, v228
	v_fma_f32 v233, v233, s15, v235
	v_fma_f32 v134, v134, v229, v228
	v_log_f32_e32 v235, v232
	v_fma_f32 v133, v133, v229, v228
	v_max_f32_e32 v133, 0x1e3ce508, v133
	v_fma_f32 v132, v132, v229, v228
	v_mul_f32_e32 v237, 0x3f317217, v235
	v_fma_f32 v237, v235, s15, -v237
	v_fmac_f32_e32 v237, 0x3377d1cf, v235
	v_fma_f32 v131, v131, v229, v228
	v_max_f32_e32 v131, 0x1e3ce508, v131
	v_fma_f32 v235, v235, s15, v237
	v_fmac_f32_e32 v228, v130, v229
	v_log_f32_e32 v237, v234
	v_max_f32_e32 v228, 0x1e3ce508, v228
	v_mul_f32_e32 v238, 0x3f317217, v237
	v_fma_f32 v238, v237, s15, -v238
	v_fmac_f32_e32 v238, 0x3377d1cf, v237
	s_nop 1
	v_fma_f32 v237, v237, s15, v238
	s_nop 0
	v_log_f32_e32 v238, v236
	s_nop 0
	v_mul_f32_e32 v239, 0x3f317217, v238
	v_fma_f32 v239, v238, s15, -v239
	v_fmac_f32_e32 v239, 0x3377d1cf, v238
	s_nop 1
	v_fma_f32 v238, v238, s15, v239
	s_nop 0
	v_log_f32_e32 v239, v225
	s_nop 0
	v_mul_f32_e32 v240, 0x3f317217, v239
	v_fma_f32 v240, v239, s15, -v240
	v_fmac_f32_e32 v240, 0x3377d1cf, v239
	s_nop 1
	v_fma_f32 v239, v239, s15, v240
	s_nop 0
	v_log_f32_e32 v240, v224
	s_nop 0
	v_mul_f32_e32 v241, 0x3f317217, v240
	v_fma_f32 v241, v240, s15, -v241
	v_fmac_f32_e32 v241, 0x3377d1cf, v240
	s_nop 1
	v_fma_f32 v240, v240, s15, v241
	s_nop 0
	v_log_f32_e32 v241, v223
	s_nop 0
	v_mul_f32_e32 v242, 0x3f317217, v241
	v_fma_f32 v242, v241, s15, -v242
	v_fmac_f32_e32 v242, 0x3377d1cf, v241
	s_nop 1
	v_fma_f32 v241, v241, s15, v242
	s_nop 0
	v_log_f32_e32 v242, v222
	s_nop 0
	v_mul_f32_e32 v243, 0x3f317217, v242
	v_fma_f32 v243, v242, s15, -v243
	v_fmac_f32_e32 v243, 0x3377d1cf, v242
	s_nop 1
	v_fma_f32 v242, v242, s15, v243
	v_mov_b32_e32 v248, v242
	v_max_f32_e32 v242, 0x1e3ce508, v135
	s_nop 1
	v_log_f32_e32 v135, v242
	s_nop 0
	v_mul_f32_e32 v243, 0x3f317217, v135
	v_fma_f32 v243, v135, s15, -v243
	v_fmac_f32_e32 v243, 0x3377d1cf, v135
	s_nop 1
	v_fma_f32 v135, v135, s15, v243
	v_max_f32_e32 v243, 0x1e3ce508, v134
	s_nop 1
	v_log_f32_e32 v134, v243
	s_nop 0
	v_mul_f32_e32 v244, 0x3f317217, v134
	v_fma_f32 v244, v134, s15, -v244
	v_fmac_f32_e32 v244, 0x3377d1cf, v134
	s_nop 1
	v_fma_f32 v134, v134, s15, v244
	s_nop 0
	v_log_f32_e32 v244, v133
	s_nop 0
	v_mul_f32_e32 v245, 0x3f317217, v244
	v_fma_f32 v245, v244, s15, -v245
	v_fmac_f32_e32 v245, 0x3377d1cf, v244
	s_nop 1
	v_fma_f32 v244, v244, s15, v245
	v_mov_b32_e32 v250, v244
	v_max_f32_e32 v244, 0x1e3ce508, v132
	s_nop 1
	v_log_f32_e32 v132, v244
	s_nop 0
	v_mul_f32_e32 v245, 0x3f317217, v132
	v_fma_f32 v245, v132, s15, -v245
	v_fmac_f32_e32 v245, 0x3377d1cf, v132
	s_nop 1
	v_fma_f32 v132, v132, s15, v245
	s_nop 0
	v_log_f32_e32 v245, v131
	s_nop 0
	v_mul_f32_e32 v246, 0x3f317217, v245
	v_fma_f32 v246, v245, s15, -v246
	v_fmac_f32_e32 v246, 0x3377d1cf, v245
	s_nop 1
	v_fma_f32 v245, v245, s15, v246
	v_mov_b32_e32 v251, v245
	s_nop 0
	v_log_f32_e32 v130, v228
	s_nop 0
	v_mul_f32_e32 v229, 0x3f317217, v130
	v_fma_f32 v229, v130, s15, -v229
	v_fmac_f32_e32 v229, 0x3377d1cf, v130
	s_nop 1
	v_fma_f32 v130, v130, s15, v229
	v_mov_b32_e32 v229, v130
	v_add_f32_e32 v130, 0, v227
	v_add_f32_e32 v245, v231, v130
	v_add_f32_e32 v246, v233, v245
	v_add_f32_e32 v247, v235, v246
	v_add_f32_e32 v237, v237, v247
	v_add_f32_e32 v238, v238, v237
	v_add_f32_e32 v239, v239, v238
	v_add_f32_e32 v240, v240, v239
	v_add_f32_e32 v241, v241, v240
	v_add_f32_e32 v248, v248, v241
	v_add_f32_e32 v249, v135, v248
	v_add_f32_e32 v231, v134, v249
	v_add_f32_e32 v233, v250, v231
	v_add_f32_e32 v235, v132, v233
	v_add_f32_e32 v227, v251, v235
	v_add_f32_e32 v229, v229, v227
	ds_write_b32 v113, v229
	s_waitcnt lgkmcnt(0)
	s_barrier
	ds_read2st64_b32 v[134:135], v136 offset1:2
	v_mov_b32_e32 v132, 0
	s_and_saveexec_b64 s[40:41], s[6:7]
	s_cbranch_execz .LBB0_106
	ds_read_b32 v250, v136 offset:1024
	v_cmp_lt_i32_e32 vcc, 1, v3
	s_mov_b64 s[14:15], 0
	s_and_saveexec_b64 s[16:17], vcc
	s_xor_b64 s[54:55], exec, s[16:17]
	s_cbranch_execz .LBB0_108
	v_cmp_eq_u32_e32 vcc, 2, v3
	s_mov_b64 s[14:15], -1
	s_and_saveexec_b64 s[62:63], vcc
	s_cbranch_execz .LBB0_102
	s_waitcnt lgkmcnt(1)
	v_add_f32_e32 v132, v134, v135
	s_xor_b64 s[14:15], exec, -1

; __device__ __forceinline__ void hgrn_pass1_all(LAS unsigned char* lds, const unsigned char* R, bf16_t* ST, float* DBUF, const float* lbp, int u0, int ustep, int tid) {
;     ...
;         HG_CUMSUM(tot)
.LBB0_130:
	s_and_b32 s10, s14, 0x180
	v_mul_f32_e32 v37, 0xbfb8aa3b, v38
	v_exp_f32_e32 v37, v37
	s_mov_b32 s14, 0x800000
	v_mul_f32_e32 v39, 0xbfb8aa3b, v39
	v_exp_f32_e32 v39, v39
	v_add_f32_e32 v37, 1.0, v37
	v_rcp_f32_e32 v37, v37
	s_mov_b32 s15, 0x3f317217
	v_add_f32_e32 v39, 1.0, v39
	v_rcp_f32_e32 v39, v39
	s_mov_b32 s16, 0x7f800000
	v_mul_f32_e32 v40, 0xbfb8aa3b, v40
	v_exp_f32_e32 v40, v40
	v_mul_f32_e32 v41, 0xbfb8aa3b, v41
	v_exp_f32_e32 v41, v41
	v_mul_f32_e32 v42, 0xbfb8aa3b, v42
	v_add_f32_e32 v40, 1.0, v40
	v_rcp_f32_e32 v40, v40
	v_add_f32_e32 v41, 1.0, v41
	v_rcp_f32_e32 v41, v41
	v_exp_f32_e32 v42, v42
	v_mul_f32_e32 v43, 0xbfb8aa3b, v43
	v_exp_f32_e32 v43, v43
	v_mul_f32_e32 v44, 0xbfb8aa3b, v44
	v_add_f32_e32 v42, 1.0, v42
	v_rcp_f32_e32 v42, v42
	v_add_f32_e32 v43, 1.0, v43
	v_rcp_f32_e32 v43, v43
	v_exp_f32_e32 v44, v44
	v_mul_f32_e32 v45, 0xbfb8aa3b, v45
	v_exp_f32_e32 v45, v45
	v_mul_f32_e32 v46, 0xbfb8aa3b, v46
	v_add_f32_e32 v44, 1.0, v44
	v_rcp_f32_e32 v44, v44
	v_add_f32_e32 v45, 1.0, v45
	v_rcp_f32_e32 v45, v45
	v_exp_f32_e32 v46, v46
	v_mul_f32_e32 v47, 0xbfb8aa3b, v47
	v_exp_f32_e32 v47, v47
	v_mul_f32_e32 v48, 0xbfb8aa3b, v48
	v_add_f32_e32 v46, 1.0, v46
	v_rcp_f32_e32 v46, v46
	v_add_f32_e32 v47, 1.0, v47
	v_rcp_f32_e32 v47, v47
	v_exp_f32_e32 v48, v48
	v_mul_f32_e32 v49, 0xbfb8aa3b, v49
	v_exp_f32_e32 v49, v49
	v_mul_f32_e32 v50, 0xbfb8aa3b, v50
	v_add_f32_e32 v48, 1.0, v48
	v_rcp_f32_e32 v48, v48
	v_add_f32_e32 v49, 1.0, v49
	v_rcp_f32_e32 v49, v49
	v_exp_f32_e32 v50, v50
	v_mul_f32_e32 v51, 0xbfb8aa3b, v51
	v_exp_f32_e32 v51, v51
	v_mul_f32_e32 v52, 0xbfb8aa3b, v52
	v_add_f32_e32 v50, 1.0, v50
	v_rcp_f32_e32 v50, v50
	v_add_f32_e32 v51, 1.0, v51
	v_rcp_f32_e32 v51, v51
	v_exp_f32_e32 v52, v52
	v_mul_f32_e32 v53, 0xbfb8aa3b, v53
	v_exp_f32_e32 v53, v53
	v_add_f32_e32 v52, 1.0, v52
	v_rcp_f32_e32 v52, v52
	v_add_f32_e32 v53, 1.0, v53
	v_rcp_f32_e32 v53, v53
	s_waitcnt vmcnt(18)
	v_sub_f32_e32 v55, 1.0, v54
	v_fma_f32 v37, v37, v55, v54
	v_max_f32_e32 v38, 0x1e3ce508, v37
	v_fma_f32 v39, v39, v55, v54
	v_max_f32_e32 v39, 0x1e3ce508, v39
	v_log_f32_e32 v37, v38
	v_fma_f32 v40, v40, v55, v54
	v_max_f32_e32 v40, 0x1e3ce508, v40
	v_fma_f32 v41, v41, v55, v54
	v_mul_f32_e32 v56, 0x3f317217, v37
	v_fma_f32 v56, v37, s15, -v56
	v_fmac_f32_e32 v56, 0x3377d1cf, v37
	v_max_f32_e32 v41, 0x1e3ce508, v41
	v_fma_f32 v42, v42, v55, v54
	v_fma_f32 v37, v37, s15, v56
	v_max_f32_e32 v42, 0x1e3ce508, v42
	v_log_f32_e32 v56, v39
	v_fma_f32 v43, v43, v55, v54
	v_max_f32_e32 v43, 0x1e3ce508, v43
	v_fma_f32 v44, v44, v55, v54
	v_mul_f32_e32 v57, 0x3f317217, v56
	v_fma_f32 v57, v56, s15, -v57
	v_fmac_f32_e32 v57, 0x3377d1cf, v56
	v_max_f32_e32 v44, 0x1e3ce508, v44
	v_fma_f32 v45, v45, v55, v54
	v_fma_f32 v56, v56, s15, v57
	v_max_f32_e32 v45, 0x1e3ce508, v45
	v_log_f32_e32 v57, v40
	v_fma_f32 v46, v46, v55, v54
	v_max_f32_e32 v46, 0x1e3ce508, v46
	v_fma_f32 v47, v47, v55, v54
	v_mul_f32_e32 v58, 0x3f317217, v57
	v_fma_f32 v58, v57, s15, -v58
	v_fmac_f32_e32 v58, 0x3377d1cf, v57
	v_max_f32_e32 v47, 0x1e3ce508, v47
	v_fma_f32 v48, v48, v55, v54
	v_fma_f32 v57, v57, s15, v58
	v_max_f32_e32 v48, 0x1e3ce508, v48
	v_log_f32_e32 v58, v41
	v_fma_f32 v49, v49, v55, v54
	v_max_f32_e32 v49, 0x1e3ce508, v49
	v_fma_f32 v50, v50, v55, v54
	v_mul_f32_e32 v59, 0x3f317217, v58
	v_fma_f32 v59, v58, s15, -v59
	v_fmac_f32_e32 v59, 0x3377d1cf, v58
	v_max_f32_e32 v50, 0x1e3ce508, v50
	v_fma_f32 v51, v51, v55, v54
	v_fma_f32 v58, v58, s15, v59
	v_max_f32_e32 v51, 0x1e3ce508, v51
	v_log_f32_e32 v59, v42
	v_fma_f32 v52, v52, v55, v54
	v_max_f32_e32 v52, 0x1e3ce508, v52
	v_fmac_f32_e32 v54, v53, v55
	v_mul_f32_e32 v60, 0x3f317217, v59
	v_fma_f32 v60, v59, s15, -v60
	v_fmac_f32_e32 v60, 0x3377d1cf, v59
	v_max_f32_e32 v53, 0x1e3ce508, v54
	s_nop 0
	v_fma_f32 v59, v59, s15, v60
	s_nop 0
	v_log_f32_e32 v60, v43
	s_nop 0
	v_mul_f32_e32 v61, 0x3f317217, v60
	v_fma_f32 v61, v60, s15, -v61
	v_fmac_f32_e32 v61, 0x3377d1cf, v60
	s_nop 1
	v_fma_f32 v60, v60, s15, v61
	s_nop 0
	v_log_f32_e32 v61, v44
	s_nop 0
	v_mul_f32_e32 v86, 0x3f317217, v61
	v_fma_f32 v86, v61, s15, -v86
	v_fmac_f32_e32 v86, 0x3377d1cf, v61
	s_nop 1
	v_fma_f32 v61, v61, s15, v86
	s_nop 0
	v_log_f32_e32 v86, v45
	s_nop 0
	v_mul_f32_e32 v87, 0x3f317217, v86
	v_fma_f32 v87, v86, s15, -v87
	v_fmac_f32_e32 v87, 0x3377d1cf, v86
	s_nop 1
	v_fma_f32 v86, v86, s15, v87
	s_nop 0
	v_log_f32_e32 v87, v46
	s_nop 0
	v_mul_f32_e32 v88, 0x3f317217, v87
	v_fma_f32 v88, v87, s15, -v88
	v_fmac_f32_e32 v88, 0x3377d1cf, v87
	s_nop 1
	v_fma_f32 v87, v87, s15, v88
	s_nop 0
	v_log_f32_e32 v88, v47
	s_nop 0
	v_mul_f32_e32 v89, 0x3f317217, v88
	v_fma_f32 v89, v88, s15, -v89
	v_fmac_f32_e32 v89, 0x3377d1cf, v88
	s_nop 1
	v_fma_f32 v88, v88, s15, v89
	v_mov_b32_e32 v94, v88
	s_nop 0
	v_log_f32_e32 v88, v48
	s_nop 0
	v_mul_f32_e32 v89, 0x3f317217, v88
	v_fma_f32 v89, v88, s15, -v89
	v_fmac_f32_e32 v89, 0x3377d1cf, v88
	s_nop 1
	v_fma_f32 v88, v88, s15, v89
	v_mov_b32_e32 v95, v88
	s_nop 0
	v_log_f32_e32 v88, v49
	s_nop 0
	v_mul_f32_e32 v89, 0x3f317217, v88
	v_fma_f32 v89, v88, s15, -v89
	v_fmac_f32_e32 v89, 0x3377d1cf, v88
	s_nop 1
	v_fma_f32 v88, v88, s15, v89
	v_mov_b32_e32 v96, v88
	s_nop 0
	v_log_f32_e32 v88, v50
	s_nop 0
	v_mul_f32_e32 v89, 0x3f317217, v88
	v_fma_f32 v89, v88, s15, -v89
	v_fmac_f32_e32 v89, 0x3377d1cf, v88
	s_nop 1
	v_fma_f32 v88, v88, s15, v89
	v_mov_b32_e32 v97, v88
	s_nop 0
	v_log_f32_e32 v88, v51
	s_nop 0
	v_mul_f32_e32 v89, 0x3f317217, v88
	v_fma_f32 v89, v88, s15, -v89
	v_fmac_f32_e32 v89, 0x3377d1cf, v88
	s_nop 1
	v_fma_f32 v88, v88, s15, v89
	v_mov_b32_e32 v98, v88
	s_nop 0
	v_log_f32_e32 v88, v52
	s_nop 0
	v_mul_f32_e32 v89, 0x3f317217, v88
	v_fma_f32 v89, v88, s15, -v89
	v_fmac_f32_e32 v89, 0x3377d1cf, v88
	s_nop 1
	v_fma_f32 v88, v88, s15, v89
	v_mov_b32_e32 v99, v88
	s_nop 0
	v_log_f32_e32 v54, v53
	s_nop 0
	v_mul_f32_e32 v55, 0x3f317217, v54
	v_fma_f32 v55, v54, s15, -v55
	v_fmac_f32_e32 v55, 0x3377d1cf, v54
	s_nop 1
	v_fma_f32 v54, v54, s15, v55
	v_mov_b32_e32 v55, v54
	v_add_f32_e32 v54, 0, v37
	v_add_f32_e32 v88, v56, v54
	v_add_f32_e32 v89, v57, v88
	v_add_f32_e32 v90, v58, v89
	v_add_f32_e32 v91, v59, v90
	v_add_f32_e32 v92, v60, v91
	v_add_f32_e32 v93, v61, v92
	v_add_f32_e32 v86, v86, v93
	v_add_f32_e32 v87, v87, v86
	v_add_f32_e32 v94, v94, v87
	v_add_f32_e32 v95, v95, v94
	v_add_f32_e32 v96, v96, v95
	v_add_f32_e32 v97, v97, v96
	v_add_f32_e32 v98, v98, v97
	v_add_f32_e32 v37, v99, v98
	v_add_f32_e32 v55, v55, v37
	ds_write_b32 v25, v55 offset:36864
	s_waitcnt lgkmcnt(0)
	s_barrier
	ds_read2st64_b32 v[56:57], v64 offset0:144 offset1:146
	ds_read2st64_b32 v[60:61], v64 offset0:148 offset1:150
	v_mov_b32_e32 v59, 0
	s_and_saveexec_b64 s[10:11], s[8:9]
	s_cbranch_execz .LBB0_138
	v_cmp_lt_i32_e32 vcc, 1, v63
	s_mov_b64 s[14:15], 0
	s_and_saveexec_b64 s[16:17], vcc
	s_xor_b64 s[28:29], exec, s[16:17]
	s_cbranch_execz .LBB0_140
	v_cmp_eq_u32_e32 vcc, 2, v63
	s_mov_b64 s[14:15], -1
	s_and_saveexec_b64 s[30:31], vcc
	s_cbranch_execz .LBB0_134
	s_waitcnt lgkmcnt(1)
	v_add_f32_e32 v59, v56, v57
	s_xor_b64 s[14:15], exec, -1
